# P0a transposes: all 32 row loads of a 64x32 tile issued before draining (was 2 rounds of 16 each drained to vmcnt(0)), on top of v028
# speedup vs baseline: 1.0035x; 1.0028x over previous
.LBB0_18:
	s_mov_b32 s62, 0x4000
	s_mov_b32 s66, 0x8000
	s_mov_b32 s67, 0
	v_mad_u32_u24 v142, v38, s21, v44
	v_mad_u64_u32 v[140:141], s[64:65], v4, s62, v[2:3]
	global_load_dword v100, v[140:141], off
	v_lshl_add_u64 v[140:141], v[140:141], 0, s[66:67]
	global_load_dword v101, v[140:141], off
	v_lshl_add_u64 v[140:141], v[140:141], 0, s[66:67]
	global_load_dword v102, v[140:141], off
	v_lshl_add_u64 v[140:141], v[140:141], 0, s[66:67]
	global_load_dword v103, v[140:141], off
	v_lshl_add_u64 v[140:141], v[140:141], 0, s[66:67]
	global_load_dword v104, v[140:141], off
	v_lshl_add_u64 v[140:141], v[140:141], 0, s[66:67]
	global_load_dword v105, v[140:141], off
	v_lshl_add_u64 v[140:141], v[140:141], 0, s[66:67]
	global_load_dword v106, v[140:141], off
	v_lshl_add_u64 v[140:141], v[140:141], 0, s[66:67]
	global_load_dword v107, v[140:141], off
	v_lshl_add_u64 v[140:141], v[140:141], 0, s[66:67]
	global_load_dword v108, v[140:141], off
	v_lshl_add_u64 v[140:141], v[140:141], 0, s[66:67]
	global_load_dword v109, v[140:141], off
	v_lshl_add_u64 v[140:141], v[140:141], 0, s[66:67]
	global_load_dword v110, v[140:141], off
	v_lshl_add_u64 v[140:141], v[140:141], 0, s[66:67]
	global_load_dword v111, v[140:141], off
	v_lshl_add_u64 v[140:141], v[140:141], 0, s[66:67]
	global_load_dword v112, v[140:141], off
	v_lshl_add_u64 v[140:141], v[140:141], 0, s[66:67]
	global_load_dword v113, v[140:141], off
	v_lshl_add_u64 v[140:141], v[140:141], 0, s[66:67]
	global_load_dword v114, v[140:141], off
	v_lshl_add_u64 v[140:141], v[140:141], 0, s[66:67]
	global_load_dword v115, v[140:141], off
	v_lshl_add_u64 v[140:141], v[140:141], 0, s[66:67]
	global_load_dword v116, v[140:141], off
	v_lshl_add_u64 v[140:141], v[140:141], 0, s[66:67]
	global_load_dword v117, v[140:141], off
	v_lshl_add_u64 v[140:141], v[140:141], 0, s[66:67]
	global_load_dword v118, v[140:141], off
	v_lshl_add_u64 v[140:141], v[140:141], 0, s[66:67]
	global_load_dword v119, v[140:141], off
	v_lshl_add_u64 v[140:141], v[140:141], 0, s[66:67]
	global_load_dword v120, v[140:141], off
	v_lshl_add_u64 v[140:141], v[140:141], 0, s[66:67]
	global_load_dword v121, v[140:141], off
	v_lshl_add_u64 v[140:141], v[140:141], 0, s[66:67]
	global_load_dword v122, v[140:141], off
	v_lshl_add_u64 v[140:141], v[140:141], 0, s[66:67]
	global_load_dword v123, v[140:141], off
	v_lshl_add_u64 v[140:141], v[140:141], 0, s[66:67]
	global_load_dword v124, v[140:141], off
	v_lshl_add_u64 v[140:141], v[140:141], 0, s[66:67]
	global_load_dword v125, v[140:141], off
	v_lshl_add_u64 v[140:141], v[140:141], 0, s[66:67]
	global_load_dword v126, v[140:141], off
	v_lshl_add_u64 v[140:141], v[140:141], 0, s[66:67]
	global_load_dword v127, v[140:141], off
	v_lshl_add_u64 v[140:141], v[140:141], 0, s[66:67]
	global_load_dword v128, v[140:141], off
	v_lshl_add_u64 v[140:141], v[140:141], 0, s[66:67]
	global_load_dword v129, v[140:141], off
	v_lshl_add_u64 v[140:141], v[140:141], 0, s[66:67]
	global_load_dword v130, v[140:141], off
	v_lshl_add_u64 v[140:141], v[140:141], 0, s[66:67]
	global_load_dword v131, v[140:141], off
	s_waitcnt vmcnt(28)
	v_pk_mul_f32 v[100:101], v[100:101], s[20:21] op_sel_hi:[1,0]
	v_pk_mul_f32 v[102:103], v[102:103], s[20:21] op_sel_hi:[1,0]
	ds_write_b32 v142, v100
	ds_write_b32 v142, v101 offset:264
	ds_write_b32 v142, v102 offset:528
	ds_write_b32 v142, v103 offset:792
	s_waitcnt vmcnt(24)
	v_pk_mul_f32 v[104:105], v[104:105], s[20:21] op_sel_hi:[1,0]
	v_pk_mul_f32 v[106:107], v[106:107], s[20:21] op_sel_hi:[1,0]
	ds_write_b32 v142, v104 offset:1056
	ds_write_b32 v142, v105 offset:1320
	ds_write_b32 v142, v106 offset:1584
	ds_write_b32 v142, v107 offset:1848
	s_waitcnt vmcnt(20)
	v_pk_mul_f32 v[108:109], v[108:109], s[20:21] op_sel_hi:[1,0]
	v_pk_mul_f32 v[110:111], v[110:111], s[20:21] op_sel_hi:[1,0]
	ds_write_b32 v142, v108 offset:2112
	ds_write_b32 v142, v109 offset:2376
	ds_write_b32 v142, v110 offset:2640
	ds_write_b32 v142, v111 offset:2904
	s_waitcnt vmcnt(16)
	v_pk_mul_f32 v[112:113], v[112:113], s[20:21] op_sel_hi:[1,0]
	v_pk_mul_f32 v[114:115], v[114:115], s[20:21] op_sel_hi:[1,0]
	ds_write_b32 v142, v112 offset:3168
	ds_write_b32 v142, v113 offset:3432
	ds_write_b32 v142, v114 offset:3696
	ds_write_b32 v142, v115 offset:3960
	s_waitcnt vmcnt(12)
	v_pk_mul_f32 v[116:117], v[116:117], s[20:21] op_sel_hi:[1,0]
	v_pk_mul_f32 v[118:119], v[118:119], s[20:21] op_sel_hi:[1,0]
	ds_write_b32 v142, v116 offset:4224
	ds_write_b32 v142, v117 offset:4488
	ds_write_b32 v142, v118 offset:4752
	ds_write_b32 v142, v119 offset:5016
	s_waitcnt vmcnt(8)
	v_pk_mul_f32 v[120:121], v[120:121], s[20:21] op_sel_hi:[1,0]
	v_pk_mul_f32 v[122:123], v[122:123], s[20:21] op_sel_hi:[1,0]
	ds_write_b32 v142, v120 offset:5280
	ds_write_b32 v142, v121 offset:5544
	ds_write_b32 v142, v122 offset:5808
	ds_write_b32 v142, v123 offset:6072
	s_waitcnt vmcnt(4)
	v_pk_mul_f32 v[124:125], v[124:125], s[20:21] op_sel_hi:[1,0]
	v_pk_mul_f32 v[126:127], v[126:127], s[20:21] op_sel_hi:[1,0]
	ds_write_b32 v142, v124 offset:6336
	ds_write_b32 v142, v125 offset:6600
	ds_write_b32 v142, v126 offset:6864
	ds_write_b32 v142, v127 offset:7128
	s_waitcnt vmcnt(0)
	v_pk_mul_f32 v[128:129], v[128:129], s[20:21] op_sel_hi:[1,0]
	v_pk_mul_f32 v[130:131], v[130:131], s[20:21] op_sel_hi:[1,0]
	ds_write_b32 v142, v128 offset:7392
	ds_write_b32 v142, v129 offset:7656
	ds_write_b32 v142, v130 offset:7920
	ds_write_b32 v142, v131 offset:8184
	s_waitcnt lgkmcnt(0)
	ds_read2_b32 v[6:7], v59 offset1:16
	ds_read2_b32 v[8:9], v59 offset0:33 offset1:49
	ds_read2_b32 v[10:11], v59 offset0:66 offset1:82
	ds_read2_b32 v[12:13], v59 offset0:99 offset1:115
	ds_read2_b32 v[16:17], v59 offset0:132 offset1:148
	ds_read2_b32 v[18:19], v59 offset0:165 offset1:181
	ds_read2_b32 v[20:21], v59 offset0:198 offset1:214
	ds_read2_b32 v[22:23], v59 offset0:231 offset1:247
	s_waitcnt lgkmcnt(7)
	v_max_f32_e32 v2, v6, v6
	s_waitcnt lgkmcnt(6)
	v_max_f32_e32 v3, v8, v8
	v_med3_f32 v6, v2, s39, v77
	v_med3_f32 v3, v3, s39, v77
	v_mov_b32_e32 v2, v35
	v_cvt_pk_fp8_f32 v2, v6, v3
	s_waitcnt lgkmcnt(5)
	v_max_f32_e32 v4, v10, v10
	s_waitcnt lgkmcnt(4)
	v_max_f32_e32 v5, v12, v12
	v_med3_f32 v4, v4, s39, v77
	v_med3_f32 v5, v5, s39, v77
	v_cvt_pk_fp8_f32 v2, v4, v5 op_sel:[0,0,1]
	s_waitcnt lgkmcnt(3)
	v_max_f32_e32 v3, v16, v16
	s_waitcnt lgkmcnt(2)
	v_max_f32_e32 v4, v18, v18
	v_med3_f32 v8, v3, s39, v77
	v_med3_f32 v4, v4, s39, v77
	v_mov_b32_e32 v3, v35
	v_cvt_pk_fp8_f32 v3, v8, v4
	v_add_u32_e32 v8, 0x400, v59
	ds_read2_b32 v[24:25], v8 offset0:8 offset1:24
	ds_read2_b32 v[26:27], v8 offset0:41 offset1:57
	ds_read2_b32 v[28:29], v8 offset0:74 offset1:90
	ds_read2_b32 v[30:31], v8 offset0:107 offset1:123
	s_waitcnt lgkmcnt(5)
	v_max_f32_e32 v5, v20, v20
	s_waitcnt lgkmcnt(4)
	v_max_f32_e32 v6, v22, v22
	v_med3_f32 v5, v5, s39, v77
	v_med3_f32 v6, v6, s39, v77
	v_cvt_pk_fp8_f32 v3, v5, v6 op_sel:[0,0,1]
	s_waitcnt lgkmcnt(3)
	v_max_f32_e32 v4, v24, v24
	s_waitcnt lgkmcnt(2)
	v_max_f32_e32 v5, v26, v26
	v_med3_f32 v12, v4, s39, v77
	v_med3_f32 v5, v5, s39, v77
	v_mov_b32_e32 v4, v35
	v_cvt_pk_fp8_f32 v4, v12, v5
	ds_read2_b32 v[32:33], v8 offset0:140 offset1:156
	ds_read2_b32 v[80:81], v8 offset0:173 offset1:189
	ds_read2_b32 v[82:83], v8 offset0:206 offset1:222
	s_waitcnt lgkmcnt(4)
	v_max_f32_e32 v6, v28, v28
	s_waitcnt lgkmcnt(3)
	v_max_f32_e32 v10, v30, v30
	v_med3_f32 v6, v6, s39, v77
	v_med3_f32 v5, v10, s39, v77
	ds_read2_b32 v[84:85], v8 offset0:239 offset1:255
	v_cvt_pk_fp8_f32 v4, v6, v5 op_sel:[0,0,1]
	s_waitcnt lgkmcnt(3)
	v_max_f32_e32 v5, v32, v32
	s_waitcnt lgkmcnt(2)
	v_max_f32_e32 v6, v80, v80
	v_med3_f32 v8, v5, s39, v77
	v_med3_f32 v6, v6, s39, v77
	v_mov_b32_e32 v5, v35
	v_cvt_pk_fp8_f32 v5, v8, v6
	s_waitcnt lgkmcnt(1)
	v_max_f32_e32 v10, v82, v82
	s_waitcnt lgkmcnt(0)
	v_max_f32_e32 v6, v84, v84
	v_med3_f32 v8, v10, s39, v77
	v_med3_f32 v6, v6, s39, v77
	v_cvt_pk_fp8_f32 v5, v8, v6 op_sel:[0,0,1]
	v_or_b32_e32 v6, s6, v45
	v_lshl_add_u64 v[14:15], v[46:47], 0, s[16:17]
	v_lshlrev_b32_e32 v34, 14, v6
	v_lshl_add_u64 v[86:87], v[14:15], 0, v[34:35]
	global_store_dwordx4 v[86:87], v[2:5], off
	s_nop 1
	v_max_f32_e32 v2, v7, v7
	v_max_f32_e32 v3, v9, v9
	v_med3_f32 v5, v2, s39, v77
	v_med3_f32 v3, v3, s39, v77
	v_mov_b32_e32 v2, v35
	v_cvt_pk_fp8_f32 v2, v5, v3
	v_max_f32_e32 v4, v11, v11
	v_max_f32_e32 v3, v13, v13
	v_med3_f32 v4, v4, s39, v77
	v_med3_f32 v3, v3, s39, v77
	v_cvt_pk_fp8_f32 v2, v4, v3 op_sel:[0,0,1]
	v_max_f32_e32 v3, v17, v17
	v_max_f32_e32 v4, v19, v19
	v_med3_f32 v6, v3, s39, v77
	v_med3_f32 v4, v4, s39, v77
	v_mov_b32_e32 v3, v35
	v_cvt_pk_fp8_f32 v3, v6, v4
	v_max_f32_e32 v5, v21, v21
	v_max_f32_e32 v4, v23, v23
	v_med3_f32 v5, v5, s39, v77
	v_med3_f32 v4, v4, s39, v77
	v_cvt_pk_fp8_f32 v3, v5, v4 op_sel:[0,0,1]
	v_max_f32_e32 v4, v25, v25
	v_max_f32_e32 v5, v27, v27
	v_med3_f32 v7, v4, s39, v77
	v_med3_f32 v5, v5, s39, v77
	v_mov_b32_e32 v4, v35
	v_cvt_pk_fp8_f32 v4, v7, v5
	v_max_f32_e32 v6, v29, v29
	v_max_f32_e32 v5, v31, v31
	v_med3_f32 v6, v6, s39, v77
	v_med3_f32 v5, v5, s39, v77
	v_cvt_pk_fp8_f32 v4, v6, v5 op_sel:[0,0,1]
	v_max_f32_e32 v5, v33, v33
	v_max_f32_e32 v6, v81, v81
	v_med3_f32 v8, v5, s39, v77
	v_med3_f32 v6, v6, s39, v77
	v_mov_b32_e32 v5, v35
	v_cvt_pk_fp8_f32 v5, v8, v6
	v_max_f32_e32 v7, v83, v83
	v_max_f32_e32 v6, v85, v85
	v_med3_f32 v7, v7, s39, v77
	v_med3_f32 v6, v6, s39, v77
	v_cvt_pk_fp8_f32 v5, v7, v6 op_sel:[0,0,1]
	v_or_b32_e32 v6, s6, v62
	v_lshlrev_b32_e32 v34, 14, v6
	v_lshl_add_u64 v[6:7], v[14:15], 0, v[34:35]
	global_store_dwordx4 v[6:7], v[2:5], off
	s_waitcnt lgkmcnt(0)
	s_mov_b64 s[6:7], 0

.LBB0_22:
	s_mov_b32 s62, 0x10000
	s_mov_b32 s66, 0x20000
	s_mov_b32 s67, 0
	v_mad_u32_u24 v142, v38, s21, v44
	v_mad_u64_u32 v[140:141], s[64:65], v4, s62, v[2:3]
	global_load_dword v100, v[140:141], off
	v_lshl_add_u64 v[140:141], v[140:141], 0, s[66:67]
	global_load_dword v101, v[140:141], off
	v_lshl_add_u64 v[140:141], v[140:141], 0, s[66:67]
	global_load_dword v102, v[140:141], off
	v_lshl_add_u64 v[140:141], v[140:141], 0, s[66:67]
	global_load_dword v103, v[140:141], off
	v_lshl_add_u64 v[140:141], v[140:141], 0, s[66:67]
	global_load_dword v104, v[140:141], off
	v_lshl_add_u64 v[140:141], v[140:141], 0, s[66:67]
	global_load_dword v105, v[140:141], off
	v_lshl_add_u64 v[140:141], v[140:141], 0, s[66:67]
	global_load_dword v106, v[140:141], off
	v_lshl_add_u64 v[140:141], v[140:141], 0, s[66:67]
	global_load_dword v107, v[140:141], off
	v_lshl_add_u64 v[140:141], v[140:141], 0, s[66:67]
	global_load_dword v108, v[140:141], off
	v_lshl_add_u64 v[140:141], v[140:141], 0, s[66:67]
	global_load_dword v109, v[140:141], off
	v_lshl_add_u64 v[140:141], v[140:141], 0, s[66:67]
	global_load_dword v110, v[140:141], off
	v_lshl_add_u64 v[140:141], v[140:141], 0, s[66:67]
	global_load_dword v111, v[140:141], off
	v_lshl_add_u64 v[140:141], v[140:141], 0, s[66:67]
	global_load_dword v112, v[140:141], off
	v_lshl_add_u64 v[140:141], v[140:141], 0, s[66:67]
	global_load_dword v113, v[140:141], off
	v_lshl_add_u64 v[140:141], v[140:141], 0, s[66:67]
	global_load_dword v114, v[140:141], off
	v_lshl_add_u64 v[140:141], v[140:141], 0, s[66:67]
	global_load_dword v115, v[140:141], off
	v_lshl_add_u64 v[140:141], v[140:141], 0, s[66:67]
	global_load_dword v116, v[140:141], off
	v_lshl_add_u64 v[140:141], v[140:141], 0, s[66:67]
	global_load_dword v117, v[140:141], off
	v_lshl_add_u64 v[140:141], v[140:141], 0, s[66:67]
	global_load_dword v118, v[140:141], off
	v_lshl_add_u64 v[140:141], v[140:141], 0, s[66:67]
	global_load_dword v119, v[140:141], off
	v_lshl_add_u64 v[140:141], v[140:141], 0, s[66:67]
	global_load_dword v120, v[140:141], off
	v_lshl_add_u64 v[140:141], v[140:141], 0, s[66:67]
	global_load_dword v121, v[140:141], off
	v_lshl_add_u64 v[140:141], v[140:141], 0, s[66:67]
	global_load_dword v122, v[140:141], off
	v_lshl_add_u64 v[140:141], v[140:141], 0, s[66:67]
	global_load_dword v123, v[140:141], off
	v_lshl_add_u64 v[140:141], v[140:141], 0, s[66:67]
	global_load_dword v124, v[140:141], off
	v_lshl_add_u64 v[140:141], v[140:141], 0, s[66:67]
	global_load_dword v125, v[140:141], off
	v_lshl_add_u64 v[140:141], v[140:141], 0, s[66:67]
	global_load_dword v126, v[140:141], off
	v_lshl_add_u64 v[140:141], v[140:141], 0, s[66:67]
	global_load_dword v127, v[140:141], off
	v_lshl_add_u64 v[140:141], v[140:141], 0, s[66:67]
	global_load_dword v128, v[140:141], off
	v_lshl_add_u64 v[140:141], v[140:141], 0, s[66:67]
	global_load_dword v129, v[140:141], off
	v_lshl_add_u64 v[140:141], v[140:141], 0, s[66:67]
	global_load_dword v130, v[140:141], off
	v_lshl_add_u64 v[140:141], v[140:141], 0, s[66:67]
	global_load_dword v131, v[140:141], off
	s_waitcnt vmcnt(28)
	ds_write_b32 v142, v100
	ds_write_b32 v142, v101 offset:264
	ds_write_b32 v142, v102 offset:528
	ds_write_b32 v142, v103 offset:792
	s_waitcnt vmcnt(24)
	ds_write_b32 v142, v104 offset:1056
	ds_write_b32 v142, v105 offset:1320
	ds_write_b32 v142, v106 offset:1584
	ds_write_b32 v142, v107 offset:1848
	s_waitcnt vmcnt(20)
	ds_write_b32 v142, v108 offset:2112
	ds_write_b32 v142, v109 offset:2376
	ds_write_b32 v142, v110 offset:2640
	ds_write_b32 v142, v111 offset:2904
	s_waitcnt vmcnt(16)
	ds_write_b32 v142, v112 offset:3168
	ds_write_b32 v142, v113 offset:3432
	ds_write_b32 v142, v114 offset:3696
	ds_write_b32 v142, v115 offset:3960
	s_waitcnt vmcnt(12)
	ds_write_b32 v142, v116 offset:4224
	ds_write_b32 v142, v117 offset:4488
	ds_write_b32 v142, v118 offset:4752
	ds_write_b32 v142, v119 offset:5016
	s_waitcnt vmcnt(8)
	ds_write_b32 v142, v120 offset:5280
	ds_write_b32 v142, v121 offset:5544
	ds_write_b32 v142, v122 offset:5808
	ds_write_b32 v142, v123 offset:6072
	s_waitcnt vmcnt(4)
	ds_write_b32 v142, v124 offset:6336
	ds_write_b32 v142, v125 offset:6600
	ds_write_b32 v142, v126 offset:6864
	ds_write_b32 v142, v127 offset:7128
	s_waitcnt vmcnt(0)
	ds_write_b32 v142, v128 offset:7392
	ds_write_b32 v142, v129 offset:7656
	ds_write_b32 v142, v130 offset:7920
	ds_write_b32 v142, v131 offset:8184
	s_waitcnt lgkmcnt(0)
	ds_read2_b32 v[2:3], v63 offset1:33
	v_add_u32_e32 v16, 0x800, v63
	v_add_u32_e32 v18, 0x400, v63
	v_add_u32_e32 v19, 0xc00, v63
	ds_read2_b32 v[4:5], v16 offset0:16 offset1:49
	ds_read2_b32 v[6:7], v63 offset0:66 offset1:99
	ds_read2_b32 v[8:9], v16 offset0:82 offset1:115
	ds_read2_b32 v[10:11], v63 offset0:132 offset1:165
	ds_read2_b32 v[12:13], v16 offset0:148 offset1:181
	ds_read2_b32 v[14:15], v63 offset0:198 offset1:231
	ds_read2_b32 v[16:17], v16 offset0:214 offset1:247
	ds_read2_b32 v[26:27], v18 offset0:8 offset1:41
	ds_read2_b32 v[28:29], v19 offset0:24 offset1:57
	ds_read2_b32 v[30:31], v18 offset0:74 offset1:107
	ds_read2_b32 v[32:33], v19 offset0:90 offset1:123
	ds_read2_b32 v[80:81], v18 offset0:140 offset1:173
	ds_read2_b32 v[82:83], v19 offset0:156 offset1:189
	ds_read2_b32 v[84:85], v18 offset0:206 offset1:239
	ds_read2_b32 v[86:87], v19 offset0:222 offset1:255
	s_waitcnt lgkmcnt(14)
	v_max_f32_e64 v18, |v4|, |v4|
	v_max_f32_e64 v19, |v2|, |v2|
	v_max_f32_e32 v18, v19, v18
	v_max_f32_e64 v19, |v5|, |v5|
	v_max_f32_e64 v20, |v3|, |v3|
	v_max_f32_e32 v19, v20, v19
	v_max3_f32 v18, v18, 0, v19
	s_waitcnt lgkmcnt(12)
	v_max_f32_e64 v19, |v8|, |v8|
	v_max_f32_e64 v20, |v6|, |v6|
	v_max_f32_e32 v19, v20, v19
	v_max_f32_e64 v20, |v9|, |v9|
	v_max_f32_e64 v21, |v7|, |v7|
	v_max_f32_e32 v20, v21, v20
	v_max3_f32 v18, v18, v19, v20
	s_waitcnt lgkmcnt(10)
	v_max_f32_e64 v19, |v12|, |v12|
	v_max_f32_e64 v20, |v10|, |v10|
	v_max_f32_e32 v19, v20, v19
	v_max_f32_e64 v20, |v13|, |v13|
	v_max_f32_e64 v21, |v11|, |v11|
	v_max_f32_e32 v20, v21, v20
	v_max3_f32 v18, v18, v19, v20
	s_waitcnt lgkmcnt(8)
	v_max_f32_e64 v19, |v16|, |v16|
	v_max_f32_e64 v20, |v14|, |v14|
	v_max_f32_e32 v19, v20, v19
	v_max_f32_e64 v20, |v17|, |v17|
	v_max_f32_e64 v21, |v15|, |v15|
	v_max_f32_e32 v20, v21, v20
	v_max3_f32 v18, v18, v19, v20
	s_waitcnt lgkmcnt(6)
	v_max_f32_e64 v19, |v28|, |v28|
	v_max_f32_e64 v20, |v26|, |v26|
	v_max_f32_e32 v19, v20, v19
	v_max_f32_e64 v20, |v29|, |v29|
	v_max_f32_e64 v21, |v27|, |v27|
	v_max_f32_e32 v20, v21, v20
	v_max3_f32 v18, v18, v19, v20
	s_waitcnt lgkmcnt(4)
	v_max_f32_e64 v19, |v32|, |v32|
	v_max_f32_e64 v20, |v30|, |v30|
	v_max_f32_e32 v19, v20, v19
	v_max_f32_e64 v20, |v33|, |v33|
	v_max_f32_e64 v21, |v31|, |v31|
	v_max_f32_e32 v20, v21, v20
	v_max3_f32 v18, v18, v19, v20
	s_waitcnt lgkmcnt(2)
	v_max_f32_e64 v19, |v82|, |v82|
	v_max_f32_e64 v20, |v80|, |v80|
	v_max_f32_e32 v19, v20, v19
	v_max_f32_e64 v20, |v83|, |v83|
	v_max_f32_e64 v21, |v81|, |v81|
	v_max_f32_e32 v20, v21, v20
	v_max3_f32 v18, v18, v19, v20
	s_waitcnt lgkmcnt(0)
	v_max_f32_e64 v19, |v86|, |v86|
	v_max_f32_e64 v20, |v84|, |v84|
	v_max_f32_e32 v19, v20, v19
	v_max_f32_e64 v20, |v87|, |v87|
	v_max_f32_e64 v21, |v85|, |v85|
	v_max_f32_e32 v20, v21, v20
	v_max3_f32 v18, v18, v19, v20
	v_bfe_u32 v18, v18, 23, 8
	v_max_u32_e32 v34, 3, v18
	v_lshlrev_b32_e32 v18, 23, v34
	v_sub_u32_e32 v61, 0x80000000, v18
	v_mul_f32_e32 v4, v4, v61
	v_med3_f32 v18, v4, s40, v78
	v_mul_f32_e32 v4, v5, v61
	v_mul_f32_e32 v5, v8, v61
	v_med3_f32 v19, v4, s40, v78
	v_mul_f32_e32 v4, v6, v61
	v_med3_f32 v20, v5, s40, v78
	v_mul_f32_e32 v5, v7, v61
	v_mul_f32_e32 v6, v9, v61
	v_mul_f32_e32 v7, v12, v61
	v_mul_f32_e32 v8, v13, v61
	v_mul_f32_e32 v9, v16, v61
	v_med3_f32 v21, v6, s40, v78
	v_mul_f32_e32 v6, v10, v61
	v_med3_f32 v22, v7, s40, v78
	v_mul_f32_e32 v7, v11, v61
	v_med3_f32 v23, v8, s40, v78
	v_mul_f32_e32 v8, v14, v61
	v_med3_f32 v24, v9, s40, v78
	v_mul_f32_e32 v9, v15, v61
	v_mul_f32_e32 v10, v17, v61
	v_mul_f32_e32 v11, v28, v61
	v_mul_f32_e32 v12, v29, v61
	v_mul_f32_e32 v13, v32, v61
	v_mul_f32_e32 v14, v33, v61
	v_mul_f32_e32 v15, v82, v61
	v_mul_f32_e32 v16, v83, v61
	v_mul_f32_e32 v17, v86, v61
	v_mul_f32_e32 v2, v2, v61
	v_mul_f32_e32 v3, v3, v61
	v_med3_f32 v25, v10, s40, v78
	v_mul_f32_e32 v10, v26, v61
	v_med3_f32 v26, v11, s40, v78
	v_mul_f32_e32 v11, v27, v61
	v_med3_f32 v27, v12, s40, v78
	v_mul_f32_e32 v12, v30, v61
	v_med3_f32 v28, v13, s40, v78
	v_mul_f32_e32 v13, v31, v61
	v_med3_f32 v29, v14, s40, v78
	v_mul_f32_e32 v14, v80, v61
	v_med3_f32 v30, v15, s40, v78
	v_mul_f32_e32 v15, v81, v61
	v_med3_f32 v31, v16, s40, v78
	v_mul_f32_e32 v16, v84, v61
	v_med3_f32 v32, v17, s40, v78
	v_mul_f32_e32 v17, v85, v61
	v_mul_f32_e32 v33, v87, v61
	v_med3_f32 v2, v2, s40, v78
	v_med3_f32 v3, v3, s40, v78
	v_med3_f32 v4, v4, s40, v78
	v_med3_f32 v5, v5, s40, v78
	v_med3_f32 v6, v6, s40, v78
	v_med3_f32 v7, v7, s40, v78
	v_med3_f32 v8, v8, s40, v78
	v_med3_f32 v9, v9, s40, v78
	v_med3_f32 v10, v10, s40, v78
	v_med3_f32 v11, v11, s40, v78
	v_med3_f32 v12, v12, s40, v78
	v_med3_f32 v13, v13, s40, v78
	v_med3_f32 v14, v14, s40, v78
	v_med3_f32 v15, v15, s40, v78
	v_med3_f32 v16, v16, s40, v78
	v_med3_f32 v17, v17, s40, v78
	v_med3_f32 v33, v33, s40, v78
	s_and_b32 s7, 0xffff, s7
	v_cvt_scalef32_2xpk16_fp6_f32 v[2:7], v[2:17], v[18:33], 1.0
	v_mov_b32_e32 v32, v6
	v_or_b32_e32 v6, s7, v40
	v_mov_b32_e32 v33, v7
	v_lshlrev_b32_e32 v6, 12, v6
	v_mov_b32_e32 v7, v35
	v_or_b32_e32 v8, s6, v41
	v_lshl_add_u64 v[6:7], s[18:19], 0, v[6:7]
	s_and_b32 s16, s6, 0x1f80
	v_lshrrev_b32_e32 v8, 1, v8
	v_and_b32_e32 v8, 48, v8
	v_mov_b32_e32 v9, v35
	v_lshl_add_u64 v[6:7], v[6:7], 0, s[16:17]
	v_lshl_add_u64 v[6:7], v[6:7], 0, v[8:9]
	v_add_u32_e32 v34, -2, v34
	global_store_dwordx4 v[6:7], v[2:5], off
	global_store_dwordx4 v[6:7], v[32:35], off offset:64
	s_waitcnt lgkmcnt(0)

.LBB0_28:
	s_mov_b32 s62, 0x4000
	s_mov_b32 s66, 0x8000
	s_mov_b32 s67, 0
	v_mad_u32_u24 v142, v38, s21, v44
	v_mad_u64_u32 v[140:141], s[64:65], v4, s62, v[2:3]
	global_load_dword v100, v[140:141], off
	v_lshl_add_u64 v[140:141], v[140:141], 0, s[66:67]
	global_load_dword v101, v[140:141], off
	v_lshl_add_u64 v[140:141], v[140:141], 0, s[66:67]
	global_load_dword v102, v[140:141], off
	v_lshl_add_u64 v[140:141], v[140:141], 0, s[66:67]
	global_load_dword v103, v[140:141], off
	v_lshl_add_u64 v[140:141], v[140:141], 0, s[66:67]
	global_load_dword v104, v[140:141], off
	v_lshl_add_u64 v[140:141], v[140:141], 0, s[66:67]
	global_load_dword v105, v[140:141], off
	v_lshl_add_u64 v[140:141], v[140:141], 0, s[66:67]
	global_load_dword v106, v[140:141], off
	v_lshl_add_u64 v[140:141], v[140:141], 0, s[66:67]
	global_load_dword v107, v[140:141], off
	v_lshl_add_u64 v[140:141], v[140:141], 0, s[66:67]
	global_load_dword v108, v[140:141], off
	v_lshl_add_u64 v[140:141], v[140:141], 0, s[66:67]
	global_load_dword v109, v[140:141], off
	v_lshl_add_u64 v[140:141], v[140:141], 0, s[66:67]
	global_load_dword v110, v[140:141], off
	v_lshl_add_u64 v[140:141], v[140:141], 0, s[66:67]
	global_load_dword v111, v[140:141], off
	v_lshl_add_u64 v[140:141], v[140:141], 0, s[66:67]
	global_load_dword v112, v[140:141], off
	v_lshl_add_u64 v[140:141], v[140:141], 0, s[66:67]
	global_load_dword v113, v[140:141], off
	v_lshl_add_u64 v[140:141], v[140:141], 0, s[66:67]
	global_load_dword v114, v[140:141], off
	v_lshl_add_u64 v[140:141], v[140:141], 0, s[66:67]
	global_load_dword v115, v[140:141], off
	v_lshl_add_u64 v[140:141], v[140:141], 0, s[66:67]
	global_load_dword v116, v[140:141], off
	v_lshl_add_u64 v[140:141], v[140:141], 0, s[66:67]
	global_load_dword v117, v[140:141], off
	v_lshl_add_u64 v[140:141], v[140:141], 0, s[66:67]
	global_load_dword v118, v[140:141], off
	v_lshl_add_u64 v[140:141], v[140:141], 0, s[66:67]
	global_load_dword v119, v[140:141], off
	v_lshl_add_u64 v[140:141], v[140:141], 0, s[66:67]
	global_load_dword v120, v[140:141], off
	v_lshl_add_u64 v[140:141], v[140:141], 0, s[66:67]
	global_load_dword v121, v[140:141], off
	v_lshl_add_u64 v[140:141], v[140:141], 0, s[66:67]
	global_load_dword v122, v[140:141], off
	v_lshl_add_u64 v[140:141], v[140:141], 0, s[66:67]
	global_load_dword v123, v[140:141], off
	v_lshl_add_u64 v[140:141], v[140:141], 0, s[66:67]
	global_load_dword v124, v[140:141], off
	v_lshl_add_u64 v[140:141], v[140:141], 0, s[66:67]
	global_load_dword v125, v[140:141], off
	v_lshl_add_u64 v[140:141], v[140:141], 0, s[66:67]
	global_load_dword v126, v[140:141], off
	v_lshl_add_u64 v[140:141], v[140:141], 0, s[66:67]
	global_load_dword v127, v[140:141], off
	v_lshl_add_u64 v[140:141], v[140:141], 0, s[66:67]
	global_load_dword v128, v[140:141], off
	v_lshl_add_u64 v[140:141], v[140:141], 0, s[66:67]
	global_load_dword v129, v[140:141], off
	v_lshl_add_u64 v[140:141], v[140:141], 0, s[66:67]
	global_load_dword v130, v[140:141], off
	v_lshl_add_u64 v[140:141], v[140:141], 0, s[66:67]
	global_load_dword v131, v[140:141], off
	s_waitcnt vmcnt(28)
	ds_write_b32 v142, v100
	ds_write_b32 v142, v101 offset:264
	ds_write_b32 v142, v102 offset:528
	ds_write_b32 v142, v103 offset:792
	s_waitcnt vmcnt(24)
	ds_write_b32 v142, v104 offset:1056
	ds_write_b32 v142, v105 offset:1320
	ds_write_b32 v142, v106 offset:1584
	ds_write_b32 v142, v107 offset:1848
	s_waitcnt vmcnt(20)
	ds_write_b32 v142, v108 offset:2112
	ds_write_b32 v142, v109 offset:2376
	ds_write_b32 v142, v110 offset:2640
	ds_write_b32 v142, v111 offset:2904
	s_waitcnt vmcnt(16)
	ds_write_b32 v142, v112 offset:3168
	ds_write_b32 v142, v113 offset:3432
	ds_write_b32 v142, v114 offset:3696
	ds_write_b32 v142, v115 offset:3960
	s_waitcnt vmcnt(12)
	ds_write_b32 v142, v116 offset:4224
	ds_write_b32 v142, v117 offset:4488
	ds_write_b32 v142, v118 offset:4752
	ds_write_b32 v142, v119 offset:5016
	s_waitcnt vmcnt(8)
	ds_write_b32 v142, v120 offset:5280
	ds_write_b32 v142, v121 offset:5544
	ds_write_b32 v142, v122 offset:5808
	ds_write_b32 v142, v123 offset:6072
	s_waitcnt vmcnt(4)
	ds_write_b32 v142, v124 offset:6336
	ds_write_b32 v142, v125 offset:6600
	ds_write_b32 v142, v126 offset:6864
	ds_write_b32 v142, v127 offset:7128
	s_waitcnt vmcnt(0)
	ds_write_b32 v142, v128 offset:7392
	ds_write_b32 v142, v129 offset:7656
	ds_write_b32 v142, v130 offset:7920
	ds_write_b32 v142, v131 offset:8184
	s_waitcnt lgkmcnt(0)
	ds_read2_b32 v[2:3], v63 offset1:33
	v_add_u32_e32 v16, 0x800, v63
	v_add_u32_e32 v18, 0x400, v63
	v_add_u32_e32 v19, 0xc00, v63
	ds_read2_b32 v[4:5], v16 offset0:16 offset1:49
	ds_read2_b32 v[6:7], v63 offset0:66 offset1:99
	ds_read2_b32 v[8:9], v16 offset0:82 offset1:115
	ds_read2_b32 v[10:11], v63 offset0:132 offset1:165
	ds_read2_b32 v[12:13], v16 offset0:148 offset1:181
	ds_read2_b32 v[14:15], v63 offset0:198 offset1:231
	ds_read2_b32 v[16:17], v16 offset0:214 offset1:247
	ds_read2_b32 v[26:27], v18 offset0:8 offset1:41
	ds_read2_b32 v[28:29], v19 offset0:24 offset1:57
	ds_read2_b32 v[30:31], v18 offset0:74 offset1:107
	ds_read2_b32 v[32:33], v19 offset0:90 offset1:123
	ds_read2_b32 v[80:81], v18 offset0:140 offset1:173
	ds_read2_b32 v[82:83], v19 offset0:156 offset1:189
	ds_read2_b32 v[84:85], v18 offset0:206 offset1:239
	ds_read2_b32 v[86:87], v19 offset0:222 offset1:255
	s_waitcnt lgkmcnt(14)
	v_max_f32_e64 v18, |v4|, |v4|
	v_max_f32_e64 v19, |v2|, |v2|
	v_max_f32_e32 v18, v19, v18
	v_max_f32_e64 v19, |v5|, |v5|
	v_max_f32_e64 v20, |v3|, |v3|
	v_max_f32_e32 v19, v20, v19
	v_max3_f32 v18, v18, 0, v19
	s_waitcnt lgkmcnt(12)
	v_max_f32_e64 v19, |v8|, |v8|
	v_max_f32_e64 v20, |v6|, |v6|
	v_max_f32_e32 v19, v20, v19
	v_max_f32_e64 v20, |v9|, |v9|
	v_max_f32_e64 v21, |v7|, |v7|
	v_max_f32_e32 v20, v21, v20
	v_max3_f32 v18, v18, v19, v20
	s_waitcnt lgkmcnt(10)
	v_max_f32_e64 v19, |v12|, |v12|
	v_max_f32_e64 v20, |v10|, |v10|
	v_max_f32_e32 v19, v20, v19
	v_max_f32_e64 v20, |v13|, |v13|
	v_max_f32_e64 v21, |v11|, |v11|
	v_max_f32_e32 v20, v21, v20
	v_max3_f32 v18, v18, v19, v20
	s_waitcnt lgkmcnt(8)
	v_max_f32_e64 v19, |v16|, |v16|
	v_max_f32_e64 v20, |v14|, |v14|
	v_max_f32_e32 v19, v20, v19
	v_max_f32_e64 v20, |v17|, |v17|
	v_max_f32_e64 v21, |v15|, |v15|
	v_max_f32_e32 v20, v21, v20
	v_max3_f32 v18, v18, v19, v20
	s_waitcnt lgkmcnt(6)
	v_max_f32_e64 v19, |v28|, |v28|
	v_max_f32_e64 v20, |v26|, |v26|
	v_max_f32_e32 v19, v20, v19
	v_max_f32_e64 v20, |v29|, |v29|
	v_max_f32_e64 v21, |v27|, |v27|
	v_max_f32_e32 v20, v21, v20
	v_max3_f32 v18, v18, v19, v20
	s_waitcnt lgkmcnt(4)
	v_max_f32_e64 v19, |v32|, |v32|
	v_max_f32_e64 v20, |v30|, |v30|
	v_max_f32_e32 v19, v20, v19
	v_max_f32_e64 v20, |v33|, |v33|
	v_max_f32_e64 v21, |v31|, |v31|
	v_max_f32_e32 v20, v21, v20
	v_max3_f32 v18, v18, v19, v20
	s_waitcnt lgkmcnt(2)
	v_max_f32_e64 v19, |v82|, |v82|
	v_max_f32_e64 v20, |v80|, |v80|
	v_max_f32_e32 v19, v20, v19
	v_max_f32_e64 v20, |v83|, |v83|
	v_max_f32_e64 v21, |v81|, |v81|
	v_max_f32_e32 v20, v21, v20
	v_max3_f32 v18, v18, v19, v20
	s_waitcnt lgkmcnt(0)
	v_max_f32_e64 v19, |v86|, |v86|
	v_max_f32_e64 v20, |v84|, |v84|
	v_max_f32_e32 v19, v20, v19
	v_max_f32_e64 v20, |v87|, |v87|
	v_max_f32_e64 v21, |v85|, |v85|
	v_max_f32_e32 v20, v21, v20
	v_max3_f32 v18, v18, v19, v20
	v_bfe_u32 v18, v18, 23, 8
	v_max_u32_e32 v34, 3, v18
	v_lshlrev_b32_e32 v18, 23, v34
	v_sub_u32_e32 v61, 0x80000000, v18
	v_mul_f32_e32 v4, v4, v61
	v_med3_f32 v18, v4, s40, v78
	v_mul_f32_e32 v4, v5, v61
	v_mul_f32_e32 v5, v8, v61
	v_med3_f32 v19, v4, s40, v78
	v_mul_f32_e32 v4, v6, v61
	v_med3_f32 v20, v5, s40, v78
	v_mul_f32_e32 v5, v7, v61
	v_mul_f32_e32 v6, v9, v61
	v_mul_f32_e32 v7, v12, v61
	v_mul_f32_e32 v8, v13, v61
	v_mul_f32_e32 v9, v16, v61
	v_med3_f32 v21, v6, s40, v78
	v_mul_f32_e32 v6, v10, v61
	v_med3_f32 v22, v7, s40, v78
	v_mul_f32_e32 v7, v11, v61
	v_med3_f32 v23, v8, s40, v78
	v_mul_f32_e32 v8, v14, v61
	v_med3_f32 v24, v9, s40, v78
	v_mul_f32_e32 v9, v15, v61
	v_mul_f32_e32 v10, v17, v61
	v_mul_f32_e32 v11, v28, v61
	v_mul_f32_e32 v12, v29, v61
	v_mul_f32_e32 v13, v32, v61
	v_mul_f32_e32 v14, v33, v61
	v_mul_f32_e32 v15, v82, v61
	v_mul_f32_e32 v16, v83, v61
	v_mul_f32_e32 v17, v86, v61
	v_mul_f32_e32 v2, v2, v61
	v_mul_f32_e32 v3, v3, v61
	v_med3_f32 v25, v10, s40, v78
	v_mul_f32_e32 v10, v26, v61
	v_med3_f32 v26, v11, s40, v78
	v_mul_f32_e32 v11, v27, v61
	v_med3_f32 v27, v12, s40, v78
	v_mul_f32_e32 v12, v30, v61
	v_med3_f32 v28, v13, s40, v78
	v_mul_f32_e32 v13, v31, v61
	v_med3_f32 v29, v14, s40, v78
	v_mul_f32_e32 v14, v80, v61
	v_med3_f32 v30, v15, s40, v78
	v_mul_f32_e32 v15, v81, v61
	v_med3_f32 v31, v16, s40, v78
	v_mul_f32_e32 v16, v84, v61
	v_med3_f32 v32, v17, s40, v78
	v_mul_f32_e32 v17, v85, v61
	v_mul_f32_e32 v33, v87, v61
	v_med3_f32 v2, v2, s40, v78
	v_med3_f32 v3, v3, s40, v78
	v_med3_f32 v4, v4, s40, v78
	v_med3_f32 v5, v5, s40, v78
	v_med3_f32 v6, v6, s40, v78
	v_med3_f32 v7, v7, s40, v78
	v_med3_f32 v8, v8, s40, v78
	v_med3_f32 v9, v9, s40, v78
	v_med3_f32 v10, v10, s40, v78
	v_med3_f32 v11, v11, s40, v78
	v_med3_f32 v12, v12, s40, v78
	v_med3_f32 v13, v13, s40, v78
	v_med3_f32 v14, v14, s40, v78
	v_med3_f32 v15, v15, s40, v78
	v_med3_f32 v16, v16, s40, v78
	v_med3_f32 v17, v17, s40, v78
	v_med3_f32 v33, v33, s40, v78
	s_and_b32 s11, 0xffff, s11
	v_cvt_scalef32_2xpk16_fp6_f32 v[2:7], v[2:17], v[18:33], 1.0
	v_mov_b32_e32 v32, v6
	v_or_b32_e32 v6, s11, v40
	v_mov_b32_e32 v33, v7
	v_mul_u32_u24_e32 v6, 0x1800, v6
	v_mov_b32_e32 v7, v35
	v_or_b32_e32 v8, s9, v41
	v_lshl_add_u64 v[6:7], s[14:15], 0, v[6:7]
	s_and_b32 s16, s8, 0x7f80
	v_lshrrev_b32_e32 v8, 1, v8
	v_and_b32_e32 v8, 48, v8
	v_mov_b32_e32 v9, v35
	v_lshl_add_u64 v[6:7], v[6:7], 0, s[16:17]
	v_lshl_add_u64 v[6:7], v[6:7], 0, v[8:9]
	v_lshl_add_u64 v[8:9], v[6:7], 0, s[22:23]
	v_add_co_u32_e32 v6, vcc, 0x800000, v6
	v_add_u32_e32 v34, -2, v34
	s_nop 0
	v_addc_co_u32_e32 v7, vcc, 0, v7, vcc
	global_store_dwordx4 v[6:7], v[2:5], off offset:2048
	global_store_dwordx4 v[8:9], v[32:35], off offset:64
	s_waitcnt lgkmcnt(0)
	s_mov_b64 s[8:9], 0

.LBB0_32:
	s_mov_b32 s62, 0x4000
	s_mov_b32 s66, 0x8000
	s_mov_b32 s67, 0
	v_mad_u32_u24 v142, v38, s21, v44
	v_mad_u64_u32 v[140:141], s[64:65], v4, s62, v[2:3]
	global_load_dword v100, v[140:141], off
	v_lshl_add_u64 v[140:141], v[140:141], 0, s[66:67]
	global_load_dword v101, v[140:141], off
	v_lshl_add_u64 v[140:141], v[140:141], 0, s[66:67]
	global_load_dword v102, v[140:141], off
	v_lshl_add_u64 v[140:141], v[140:141], 0, s[66:67]
	global_load_dword v103, v[140:141], off
	v_lshl_add_u64 v[140:141], v[140:141], 0, s[66:67]
	global_load_dword v104, v[140:141], off
	v_lshl_add_u64 v[140:141], v[140:141], 0, s[66:67]
	global_load_dword v105, v[140:141], off
	v_lshl_add_u64 v[140:141], v[140:141], 0, s[66:67]
	global_load_dword v106, v[140:141], off
	v_lshl_add_u64 v[140:141], v[140:141], 0, s[66:67]
	global_load_dword v107, v[140:141], off
	v_lshl_add_u64 v[140:141], v[140:141], 0, s[66:67]
	global_load_dword v108, v[140:141], off
	v_lshl_add_u64 v[140:141], v[140:141], 0, s[66:67]
	global_load_dword v109, v[140:141], off
	v_lshl_add_u64 v[140:141], v[140:141], 0, s[66:67]
	global_load_dword v110, v[140:141], off
	v_lshl_add_u64 v[140:141], v[140:141], 0, s[66:67]
	global_load_dword v111, v[140:141], off
	v_lshl_add_u64 v[140:141], v[140:141], 0, s[66:67]
	global_load_dword v112, v[140:141], off
	v_lshl_add_u64 v[140:141], v[140:141], 0, s[66:67]
	global_load_dword v113, v[140:141], off
	v_lshl_add_u64 v[140:141], v[140:141], 0, s[66:67]
	global_load_dword v114, v[140:141], off
	v_lshl_add_u64 v[140:141], v[140:141], 0, s[66:67]
	global_load_dword v115, v[140:141], off
	v_lshl_add_u64 v[140:141], v[140:141], 0, s[66:67]
	global_load_dword v116, v[140:141], off
	v_lshl_add_u64 v[140:141], v[140:141], 0, s[66:67]
	global_load_dword v117, v[140:141], off
	v_lshl_add_u64 v[140:141], v[140:141], 0, s[66:67]
	global_load_dword v118, v[140:141], off
	v_lshl_add_u64 v[140:141], v[140:141], 0, s[66:67]
	global_load_dword v119, v[140:141], off
	v_lshl_add_u64 v[140:141], v[140:141], 0, s[66:67]
	global_load_dword v120, v[140:141], off
	v_lshl_add_u64 v[140:141], v[140:141], 0, s[66:67]
	global_load_dword v121, v[140:141], off
	v_lshl_add_u64 v[140:141], v[140:141], 0, s[66:67]
	global_load_dword v122, v[140:141], off
	v_lshl_add_u64 v[140:141], v[140:141], 0, s[66:67]
	global_load_dword v123, v[140:141], off
	v_lshl_add_u64 v[140:141], v[140:141], 0, s[66:67]
	global_load_dword v124, v[140:141], off
	v_lshl_add_u64 v[140:141], v[140:141], 0, s[66:67]
	global_load_dword v125, v[140:141], off
	v_lshl_add_u64 v[140:141], v[140:141], 0, s[66:67]
	global_load_dword v126, v[140:141], off
	v_lshl_add_u64 v[140:141], v[140:141], 0, s[66:67]
	global_load_dword v127, v[140:141], off
	v_lshl_add_u64 v[140:141], v[140:141], 0, s[66:67]
	global_load_dword v128, v[140:141], off
	v_lshl_add_u64 v[140:141], v[140:141], 0, s[66:67]
	global_load_dword v129, v[140:141], off
	v_lshl_add_u64 v[140:141], v[140:141], 0, s[66:67]
	global_load_dword v130, v[140:141], off
	v_lshl_add_u64 v[140:141], v[140:141], 0, s[66:67]
	global_load_dword v131, v[140:141], off
	s_waitcnt vmcnt(28)
	ds_write_b32 v142, v100
	ds_write_b32 v142, v101 offset:264
	ds_write_b32 v142, v102 offset:528
	ds_write_b32 v142, v103 offset:792
	s_waitcnt vmcnt(24)
	ds_write_b32 v142, v104 offset:1056
	ds_write_b32 v142, v105 offset:1320
	ds_write_b32 v142, v106 offset:1584
	ds_write_b32 v142, v107 offset:1848
	s_waitcnt vmcnt(20)
	ds_write_b32 v142, v108 offset:2112
	ds_write_b32 v142, v109 offset:2376
	ds_write_b32 v142, v110 offset:2640
	ds_write_b32 v142, v111 offset:2904
	s_waitcnt vmcnt(16)
	ds_write_b32 v142, v112 offset:3168
	ds_write_b32 v142, v113 offset:3432
	ds_write_b32 v142, v114 offset:3696
	ds_write_b32 v142, v115 offset:3960
	s_waitcnt vmcnt(12)
	ds_write_b32 v142, v116 offset:4224
	ds_write_b32 v142, v117 offset:4488
	ds_write_b32 v142, v118 offset:4752
	ds_write_b32 v142, v119 offset:5016
	s_waitcnt vmcnt(8)
	ds_write_b32 v142, v120 offset:5280
	ds_write_b32 v142, v121 offset:5544
	ds_write_b32 v142, v122 offset:5808
	ds_write_b32 v142, v123 offset:6072
	s_waitcnt vmcnt(4)
	ds_write_b32 v142, v124 offset:6336
	ds_write_b32 v142, v125 offset:6600
	ds_write_b32 v142, v126 offset:6864
	ds_write_b32 v142, v127 offset:7128
	s_waitcnt vmcnt(0)
	ds_write_b32 v142, v128 offset:7392
	ds_write_b32 v142, v129 offset:7656
	ds_write_b32 v142, v130 offset:7920
	ds_write_b32 v142, v131 offset:8184
	s_waitcnt lgkmcnt(0)
	ds_read2_b32 v[6:7], v65 offset1:8
	ds_read2_b32 v[10:11], v65 offset0:33 offset1:41
	ds_read2_b32 v[12:13], v65 offset0:66 offset1:74
	ds_read2_b32 v[14:15], v65 offset0:99 offset1:107
	ds_read2_b32 v[16:17], v65 offset0:132 offset1:140
	ds_read2_b32 v[18:19], v65 offset0:165 offset1:173
	s_waitcnt lgkmcnt(5)
	v_bfe_u32 v2, v6, 16, 1
	v_add3_u32 v2, v6, v2, s41
	s_waitcnt lgkmcnt(4)
	v_bfe_u32 v3, v10, 16, 1
	v_lshrrev_b32_e32 v2, 16, v2
	v_add3_u32 v3, v10, v3, s41
	v_and_or_b32 v2, v3, s42, v2
	s_waitcnt lgkmcnt(3)
	v_bfe_u32 v3, v12, 16, 1
	v_add3_u32 v3, v12, v3, s41
	s_waitcnt lgkmcnt(2)
	v_bfe_u32 v4, v14, 16, 1
	ds_read2_b32 v[20:21], v65 offset0:198 offset1:206
	v_lshrrev_b32_e32 v3, 16, v3
	v_add3_u32 v4, v14, v4, s41
	ds_read2_b32 v[22:23], v65 offset0:231 offset1:239
	v_and_or_b32 v3, v4, s42, v3
	s_waitcnt lgkmcnt(3)
	v_bfe_u32 v4, v16, 16, 1
	v_add3_u32 v4, v16, v4, s41
	s_waitcnt lgkmcnt(2)
	v_bfe_u32 v5, v18, 16, 1
	v_lshrrev_b32_e32 v4, 16, v4
	v_add3_u32 v5, v18, v5, s41
	v_and_or_b32 v4, v5, s42, v4
	s_waitcnt lgkmcnt(1)
	v_bfe_u32 v5, v20, 16, 1
	v_add3_u32 v5, v20, v5, s41
	s_waitcnt lgkmcnt(0)
	v_bfe_u32 v6, v22, 16, 1
	v_lshrrev_b32_e32 v5, 16, v5
	v_add3_u32 v6, v22, v6, s41
	v_and_or_b32 v5, v6, s42, v5
	v_or_b32_e32 v6, s8, v64
	s_lshl_b32 s16, s9, 1
	v_mul_u32_u24_e32 v6, 0xc00, v6
	v_lshl_add_u64 v[8:9], v[48:49], 0, s[16:17]
	v_lshlrev_b32_e32 v34, 1, v6
	v_lshl_add_u64 v[24:25], v[8:9], 0, v[34:35]
	global_store_dwordx4 v[24:25], v[2:5], off
	v_bfe_u32 v6, v23, 16, 1
	v_add3_u32 v6, v23, v6, s41
	v_bfe_u32 v2, v7, 16, 1
	v_add3_u32 v2, v7, v2, s41
	v_bfe_u32 v3, v11, 16, 1
	v_lshrrev_b32_e32 v2, 16, v2
	v_add3_u32 v3, v11, v3, s41
	v_and_or_b32 v2, v3, s42, v2
	v_bfe_u32 v3, v13, 16, 1
	v_add3_u32 v3, v13, v3, s41
	v_bfe_u32 v4, v15, 16, 1
	v_lshrrev_b32_e32 v3, 16, v3
	v_add3_u32 v4, v15, v4, s41
	v_and_or_b32 v3, v4, s42, v3
	v_bfe_u32 v4, v17, 16, 1
	v_add3_u32 v4, v17, v4, s41
	v_bfe_u32 v5, v19, 16, 1
	v_lshrrev_b32_e32 v4, 16, v4
	v_add3_u32 v5, v19, v5, s41
	v_and_or_b32 v4, v5, s42, v4
	v_bfe_u32 v5, v21, 16, 1
	v_add3_u32 v5, v21, v5, s41
	v_lshrrev_b32_e32 v5, 16, v5
	v_and_or_b32 v5, v6, s42, v5
	v_or_b32_e32 v6, s8, v66
	v_mul_u32_u24_e32 v10, 0xc00, v6
	v_lshlrev_b32_e32 v34, 1, v10
	ds_read2_b32 v[6:7], v65 offset0:16 offset1:24
	v_lshl_add_u64 v[10:11], v[8:9], 0, v[34:35]
	global_store_dwordx4 v[10:11], v[2:5], off
	ds_read2_b32 v[10:11], v65 offset0:49 offset1:57
	ds_read2_b32 v[12:13], v65 offset0:82 offset1:90
	ds_read2_b32 v[14:15], v65 offset0:115 offset1:123
	s_waitcnt lgkmcnt(3)
	v_bfe_u32 v2, v6, 16, 1
	v_add3_u32 v2, v6, v2, s41
	s_waitcnt lgkmcnt(2)
	v_bfe_u32 v3, v10, 16, 1
	ds_read2_b32 v[16:17], v65 offset0:148 offset1:156
	v_lshrrev_b32_e32 v2, 16, v2
	v_add3_u32 v3, v10, v3, s41
	ds_read2_b32 v[18:19], v65 offset0:181 offset1:189
	v_and_or_b32 v2, v3, s42, v2
	s_waitcnt lgkmcnt(3)
	v_bfe_u32 v3, v12, 16, 1
	v_add3_u32 v3, v12, v3, s41
	s_waitcnt lgkmcnt(2)
	v_bfe_u32 v4, v14, 16, 1
	ds_read2_b32 v[20:21], v65 offset0:214 offset1:222
	v_lshrrev_b32_e32 v3, 16, v3
	v_add3_u32 v4, v14, v4, s41
	ds_read2_b32 v[22:23], v65 offset0:247 offset1:255
	v_and_or_b32 v3, v4, s42, v3
	s_waitcnt lgkmcnt(3)
	v_bfe_u32 v4, v16, 16, 1
	v_add3_u32 v4, v16, v4, s41
	s_waitcnt lgkmcnt(2)
	v_bfe_u32 v5, v18, 16, 1
	v_lshrrev_b32_e32 v4, 16, v4
	v_add3_u32 v5, v18, v5, s41
	v_and_or_b32 v4, v5, s42, v4
	s_waitcnt lgkmcnt(1)
	v_bfe_u32 v5, v20, 16, 1
	v_add3_u32 v5, v20, v5, s41
	s_waitcnt lgkmcnt(0)
	v_bfe_u32 v6, v22, 16, 1
	v_lshrrev_b32_e32 v5, 16, v5
	v_add3_u32 v6, v22, v6, s41
	v_and_or_b32 v5, v6, s42, v5
	v_or_b32_e32 v6, s8, v67
	v_mul_u32_u24_e32 v6, 0xc00, v6
	v_lshlrev_b32_e32 v34, 1, v6
	v_lshl_add_u64 v[24:25], v[8:9], 0, v[34:35]
	global_store_dwordx4 v[24:25], v[2:5], off
	v_bfe_u32 v6, v23, 16, 1
	v_add3_u32 v6, v23, v6, s41
	v_bfe_u32 v2, v7, 16, 1
	v_add3_u32 v2, v7, v2, s41
	v_bfe_u32 v3, v11, 16, 1
	v_lshrrev_b32_e32 v2, 16, v2
	v_add3_u32 v3, v11, v3, s41
	v_and_or_b32 v2, v3, s42, v2
	v_bfe_u32 v3, v13, 16, 1
	v_add3_u32 v3, v13, v3, s41
	v_bfe_u32 v4, v15, 16, 1
	v_lshrrev_b32_e32 v3, 16, v3
	v_add3_u32 v4, v15, v4, s41
	v_and_or_b32 v3, v4, s42, v3
	v_bfe_u32 v4, v17, 16, 1
	v_add3_u32 v4, v17, v4, s41
	v_bfe_u32 v5, v19, 16, 1
	v_lshrrev_b32_e32 v4, 16, v4
	v_add3_u32 v5, v19, v5, s41
	v_and_or_b32 v4, v5, s42, v4
	v_bfe_u32 v5, v21, 16, 1
	v_add3_u32 v5, v21, v5, s41
	v_lshrrev_b32_e32 v5, 16, v5
	v_and_or_b32 v5, v6, s42, v5
	v_or_b32_e32 v6, s8, v68
	v_mul_u32_u24_e32 v6, 0xc00, v6
	v_lshlrev_b32_e32 v34, 1, v6
	v_lshl_add_u64 v[6:7], v[8:9], 0, v[34:35]
	global_store_dwordx4 v[6:7], v[2:5], off
	s_waitcnt lgkmcnt(0)

.LBB0_80:
	s_mov_b32 s62, s46
	s_lshl_b32 s66, s46, 1
	s_mov_b32 s67, 0
	v_mad_u32_u24 v142, v38, s21, v44
	v_mad_u64_u32 v[140:141], s[64:65], v2, s62, v[4:5]
	global_load_dword v100, v[140:141], off
	v_lshl_add_u64 v[140:141], v[140:141], 0, s[66:67]
	global_load_dword v101, v[140:141], off
	v_lshl_add_u64 v[140:141], v[140:141], 0, s[66:67]
	global_load_dword v102, v[140:141], off
	v_lshl_add_u64 v[140:141], v[140:141], 0, s[66:67]
	global_load_dword v103, v[140:141], off
	v_lshl_add_u64 v[140:141], v[140:141], 0, s[66:67]
	global_load_dword v104, v[140:141], off
	v_lshl_add_u64 v[140:141], v[140:141], 0, s[66:67]
	global_load_dword v105, v[140:141], off
	v_lshl_add_u64 v[140:141], v[140:141], 0, s[66:67]
	global_load_dword v106, v[140:141], off
	v_lshl_add_u64 v[140:141], v[140:141], 0, s[66:67]
	global_load_dword v107, v[140:141], off
	v_lshl_add_u64 v[140:141], v[140:141], 0, s[66:67]
	global_load_dword v108, v[140:141], off
	v_lshl_add_u64 v[140:141], v[140:141], 0, s[66:67]
	global_load_dword v109, v[140:141], off
	v_lshl_add_u64 v[140:141], v[140:141], 0, s[66:67]
	global_load_dword v110, v[140:141], off
	v_lshl_add_u64 v[140:141], v[140:141], 0, s[66:67]
	global_load_dword v111, v[140:141], off
	v_lshl_add_u64 v[140:141], v[140:141], 0, s[66:67]
	global_load_dword v112, v[140:141], off
	v_lshl_add_u64 v[140:141], v[140:141], 0, s[66:67]
	global_load_dword v113, v[140:141], off
	v_lshl_add_u64 v[140:141], v[140:141], 0, s[66:67]
	global_load_dword v114, v[140:141], off
	v_lshl_add_u64 v[140:141], v[140:141], 0, s[66:67]
	global_load_dword v115, v[140:141], off
	v_lshl_add_u64 v[140:141], v[140:141], 0, s[66:67]
	global_load_dword v116, v[140:141], off
	v_lshl_add_u64 v[140:141], v[140:141], 0, s[66:67]
	global_load_dword v117, v[140:141], off
	v_lshl_add_u64 v[140:141], v[140:141], 0, s[66:67]
	global_load_dword v118, v[140:141], off
	v_lshl_add_u64 v[140:141], v[140:141], 0, s[66:67]
	global_load_dword v119, v[140:141], off
	v_lshl_add_u64 v[140:141], v[140:141], 0, s[66:67]
	global_load_dword v120, v[140:141], off
	v_lshl_add_u64 v[140:141], v[140:141], 0, s[66:67]
	global_load_dword v121, v[140:141], off
	v_lshl_add_u64 v[140:141], v[140:141], 0, s[66:67]
	global_load_dword v122, v[140:141], off
	v_lshl_add_u64 v[140:141], v[140:141], 0, s[66:67]
	global_load_dword v123, v[140:141], off
	v_lshl_add_u64 v[140:141], v[140:141], 0, s[66:67]
	global_load_dword v124, v[140:141], off
	v_lshl_add_u64 v[140:141], v[140:141], 0, s[66:67]
	global_load_dword v125, v[140:141], off
	v_lshl_add_u64 v[140:141], v[140:141], 0, s[66:67]
	global_load_dword v126, v[140:141], off
	v_lshl_add_u64 v[140:141], v[140:141], 0, s[66:67]
	global_load_dword v127, v[140:141], off
	v_lshl_add_u64 v[140:141], v[140:141], 0, s[66:67]
	global_load_dword v128, v[140:141], off
	v_lshl_add_u64 v[140:141], v[140:141], 0, s[66:67]
	global_load_dword v129, v[140:141], off
	v_lshl_add_u64 v[140:141], v[140:141], 0, s[66:67]
	global_load_dword v130, v[140:141], off
	v_lshl_add_u64 v[140:141], v[140:141], 0, s[66:67]
	global_load_dword v131, v[140:141], off
	s_waitcnt vmcnt(28)
	v_pk_mul_f32 v[100:101], v[100:101], s[24:25] op_sel_hi:[1,0]
	v_pk_mul_f32 v[102:103], v[102:103], s[24:25] op_sel_hi:[1,0]
	ds_write_b32 v142, v100
	ds_write_b32 v142, v101 offset:264
	ds_write_b32 v142, v102 offset:528
	ds_write_b32 v142, v103 offset:792
	s_waitcnt vmcnt(24)
	v_pk_mul_f32 v[104:105], v[104:105], s[24:25] op_sel_hi:[1,0]
	v_pk_mul_f32 v[106:107], v[106:107], s[24:25] op_sel_hi:[1,0]
	ds_write_b32 v142, v104 offset:1056
	ds_write_b32 v142, v105 offset:1320
	ds_write_b32 v142, v106 offset:1584
	ds_write_b32 v142, v107 offset:1848
	s_waitcnt vmcnt(20)
	v_pk_mul_f32 v[108:109], v[108:109], s[24:25] op_sel_hi:[1,0]
	v_pk_mul_f32 v[110:111], v[110:111], s[24:25] op_sel_hi:[1,0]
	ds_write_b32 v142, v108 offset:2112
	ds_write_b32 v142, v109 offset:2376
	ds_write_b32 v142, v110 offset:2640
	ds_write_b32 v142, v111 offset:2904
	s_waitcnt vmcnt(16)
	v_pk_mul_f32 v[112:113], v[112:113], s[24:25] op_sel_hi:[1,0]
	v_pk_mul_f32 v[114:115], v[114:115], s[24:25] op_sel_hi:[1,0]
	ds_write_b32 v142, v112 offset:3168
	ds_write_b32 v142, v113 offset:3432
	ds_write_b32 v142, v114 offset:3696
	ds_write_b32 v142, v115 offset:3960
	s_waitcnt vmcnt(12)
	v_pk_mul_f32 v[116:117], v[116:117], s[24:25] op_sel_hi:[1,0]
	v_pk_mul_f32 v[118:119], v[118:119], s[24:25] op_sel_hi:[1,0]
	ds_write_b32 v142, v116 offset:4224
	ds_write_b32 v142, v117 offset:4488
	ds_write_b32 v142, v118 offset:4752
	ds_write_b32 v142, v119 offset:5016
	s_waitcnt vmcnt(8)
	v_pk_mul_f32 v[120:121], v[120:121], s[24:25] op_sel_hi:[1,0]
	v_pk_mul_f32 v[122:123], v[122:123], s[24:25] op_sel_hi:[1,0]
	ds_write_b32 v142, v120 offset:5280
	ds_write_b32 v142, v121 offset:5544
	ds_write_b32 v142, v122 offset:5808
	ds_write_b32 v142, v123 offset:6072
	s_waitcnt vmcnt(4)
	v_pk_mul_f32 v[124:125], v[124:125], s[24:25] op_sel_hi:[1,0]
	v_pk_mul_f32 v[126:127], v[126:127], s[24:25] op_sel_hi:[1,0]
	ds_write_b32 v142, v124 offset:6336
	ds_write_b32 v142, v125 offset:6600
	ds_write_b32 v142, v126 offset:6864
	ds_write_b32 v142, v127 offset:7128
	s_waitcnt vmcnt(0)
	v_pk_mul_f32 v[128:129], v[128:129], s[24:25] op_sel_hi:[1,0]
	v_pk_mul_f32 v[130:131], v[130:131], s[24:25] op_sel_hi:[1,0]
	ds_write_b32 v142, v128 offset:7392
	ds_write_b32 v142, v129 offset:7656
	ds_write_b32 v142, v130 offset:7920
	ds_write_b32 v142, v131 offset:8184
	s_waitcnt lgkmcnt(0)
	ds_read2_b32 v[8:9], v59 offset1:16
	ds_read2_b32 v[10:11], v59 offset0:33 offset1:49
	ds_read2_b32 v[12:13], v59 offset0:66 offset1:82
	ds_read2_b32 v[14:15], v59 offset0:99 offset1:115
	ds_read2_b32 v[18:19], v59 offset0:132 offset1:148
	ds_read2_b32 v[20:21], v59 offset0:165 offset1:181
	ds_read2_b32 v[22:23], v59 offset0:198 offset1:214
	ds_read2_b32 v[24:25], v59 offset0:231 offset1:247
	s_waitcnt lgkmcnt(7)
	v_max_f32_e32 v4, v8, v8
	s_waitcnt lgkmcnt(6)
	v_max_f32_e32 v5, v10, v10
	v_med3_f32 v8, v4, s39, v77
	v_med3_f32 v5, v5, s39, v77
	v_mov_b32_e32 v4, v35
	v_cvt_pk_fp8_f32 v4, v8, v5
	s_waitcnt lgkmcnt(5)
	v_max_f32_e32 v6, v12, v12
	s_waitcnt lgkmcnt(4)
	v_max_f32_e32 v7, v14, v14
	v_med3_f32 v6, v6, s39, v77
	v_med3_f32 v7, v7, s39, v77
	v_cvt_pk_fp8_f32 v4, v6, v7 op_sel:[0,0,1]
	s_waitcnt lgkmcnt(3)
	v_max_f32_e32 v5, v18, v18
	s_waitcnt lgkmcnt(2)
	v_max_f32_e32 v6, v20, v20
	v_med3_f32 v10, v5, s39, v77
	v_med3_f32 v6, v6, s39, v77
	v_mov_b32_e32 v5, v35
	v_cvt_pk_fp8_f32 v5, v10, v6
	v_add_u32_e32 v10, 0x400, v59
	ds_read2_b32 v[26:27], v10 offset0:8 offset1:24
	ds_read2_b32 v[28:29], v10 offset0:41 offset1:57
	ds_read2_b32 v[30:31], v10 offset0:74 offset1:90
	ds_read2_b32 v[32:33], v10 offset0:107 offset1:123
	s_waitcnt lgkmcnt(5)
	v_max_f32_e32 v7, v22, v22
	s_waitcnt lgkmcnt(4)
	v_max_f32_e32 v8, v24, v24
	v_med3_f32 v7, v7, s39, v77
	v_med3_f32 v8, v8, s39, v77
	v_cvt_pk_fp8_f32 v5, v7, v8 op_sel:[0,0,1]
	s_waitcnt lgkmcnt(3)
	v_max_f32_e32 v6, v26, v26
	s_waitcnt lgkmcnt(2)
	v_max_f32_e32 v7, v28, v28
	v_med3_f32 v14, v6, s39, v77
	v_med3_f32 v7, v7, s39, v77
	v_mov_b32_e32 v6, v35
	v_cvt_pk_fp8_f32 v6, v14, v7
	ds_read2_b32 v[80:81], v10 offset0:140 offset1:156
	ds_read2_b32 v[82:83], v10 offset0:173 offset1:189
	ds_read2_b32 v[84:85], v10 offset0:206 offset1:222
	s_waitcnt lgkmcnt(4)
	v_max_f32_e32 v8, v30, v30
	s_waitcnt lgkmcnt(3)
	v_max_f32_e32 v12, v32, v32
	v_med3_f32 v8, v8, s39, v77
	v_med3_f32 v7, v12, s39, v77
	ds_read2_b32 v[86:87], v10 offset0:239 offset1:255
	v_cvt_pk_fp8_f32 v6, v8, v7 op_sel:[0,0,1]
	s_waitcnt lgkmcnt(3)
	v_max_f32_e32 v7, v80, v80
	s_waitcnt lgkmcnt(2)
	v_max_f32_e32 v8, v82, v82
	v_med3_f32 v10, v7, s39, v77
	v_med3_f32 v8, v8, s39, v77
	v_mov_b32_e32 v7, v35
	v_cvt_pk_fp8_f32 v7, v10, v8
	s_waitcnt lgkmcnt(1)
	v_max_f32_e32 v12, v84, v84
	s_waitcnt lgkmcnt(0)
	v_max_f32_e32 v8, v86, v86
	v_med3_f32 v10, v12, s39, v77
	v_med3_f32 v8, v8, s39, v77
	v_cvt_pk_fp8_f32 v7, v10, v8 op_sel:[0,0,1]
	s_ashr_i32 s9, s8, 31
	v_or_b32_e32 v34, s6, v45
	v_lshl_add_u64 v[16:17], v[54:55], 0, s[8:9]
	v_lshlrev_b64 v[88:89], 12, v[34:35]
	v_lshl_add_u64 v[88:89], v[16:17], 0, v[88:89]
	global_store_dwordx4 v[88:89], v[4:7], off
	v_or_b32_e32 v34, s6, v62
	s_mov_b64 s[26:27], 0
	v_max_f32_e32 v4, v9, v9
	v_max_f32_e32 v5, v11, v11
	v_med3_f32 v7, v4, s39, v77
	v_med3_f32 v5, v5, s39, v77
	v_mov_b32_e32 v4, v35
	v_cvt_pk_fp8_f32 v4, v7, v5
	v_max_f32_e32 v6, v13, v13
	v_max_f32_e32 v5, v15, v15
	v_med3_f32 v6, v6, s39, v77
	v_med3_f32 v5, v5, s39, v77
	v_cvt_pk_fp8_f32 v4, v6, v5 op_sel:[0,0,1]
	v_max_f32_e32 v5, v19, v19
	v_max_f32_e32 v6, v21, v21
	v_med3_f32 v8, v5, s39, v77
	v_med3_f32 v6, v6, s39, v77
	v_mov_b32_e32 v5, v35
	v_cvt_pk_fp8_f32 v5, v8, v6
	v_max_f32_e32 v7, v23, v23
	v_max_f32_e32 v6, v25, v25
	v_med3_f32 v7, v7, s39, v77
	v_med3_f32 v6, v6, s39, v77
	v_cvt_pk_fp8_f32 v5, v7, v6 op_sel:[0,0,1]
	v_max_f32_e32 v6, v27, v27
	v_max_f32_e32 v7, v29, v29
	v_med3_f32 v9, v6, s39, v77
	v_med3_f32 v7, v7, s39, v77
	v_mov_b32_e32 v6, v35
	v_cvt_pk_fp8_f32 v6, v9, v7
	v_max_f32_e32 v8, v31, v31
	v_max_f32_e32 v7, v33, v33
	v_med3_f32 v8, v8, s39, v77
	v_med3_f32 v7, v7, s39, v77
	v_cvt_pk_fp8_f32 v6, v8, v7 op_sel:[0,0,1]
	v_max_f32_e32 v7, v81, v81
	v_max_f32_e32 v8, v83, v83
	v_med3_f32 v10, v7, s39, v77
	v_med3_f32 v8, v8, s39, v77
	v_mov_b32_e32 v7, v35
	v_cvt_pk_fp8_f32 v7, v10, v8
	v_max_f32_e32 v9, v85, v85
	v_max_f32_e32 v8, v87, v87
	v_med3_f32 v9, v9, s39, v77
	v_med3_f32 v8, v8, s39, v77
	v_cvt_pk_fp8_f32 v7, v9, v8 op_sel:[0,0,1]
	v_lshlrev_b64 v[8:9], 12, v[34:35]
	v_lshl_add_u64 v[8:9], v[16:17], 0, v[8:9]
	global_store_dwordx4 v[8:9], v[4:7], off
	s_waitcnt lgkmcnt(0)

.LBB0_84:
	s_mov_b32 s62, s46
	s_lshl_b32 s66, s46, 1
	s_mov_b32 s67, 0
	v_mad_u32_u24 v142, v38, s21, v44
	v_mad_u64_u32 v[140:141], s[64:65], v2, s62, v[4:5]
	global_load_dword v100, v[140:141], off
	v_lshl_add_u64 v[140:141], v[140:141], 0, s[66:67]
	global_load_dword v101, v[140:141], off
	v_lshl_add_u64 v[140:141], v[140:141], 0, s[66:67]
	global_load_dword v102, v[140:141], off
	v_lshl_add_u64 v[140:141], v[140:141], 0, s[66:67]
	global_load_dword v103, v[140:141], off
	v_lshl_add_u64 v[140:141], v[140:141], 0, s[66:67]
	global_load_dword v104, v[140:141], off
	v_lshl_add_u64 v[140:141], v[140:141], 0, s[66:67]
	global_load_dword v105, v[140:141], off
	v_lshl_add_u64 v[140:141], v[140:141], 0, s[66:67]
	global_load_dword v106, v[140:141], off
	v_lshl_add_u64 v[140:141], v[140:141], 0, s[66:67]
	global_load_dword v107, v[140:141], off
	v_lshl_add_u64 v[140:141], v[140:141], 0, s[66:67]
	global_load_dword v108, v[140:141], off
	v_lshl_add_u64 v[140:141], v[140:141], 0, s[66:67]
	global_load_dword v109, v[140:141], off
	v_lshl_add_u64 v[140:141], v[140:141], 0, s[66:67]
	global_load_dword v110, v[140:141], off
	v_lshl_add_u64 v[140:141], v[140:141], 0, s[66:67]
	global_load_dword v111, v[140:141], off
	v_lshl_add_u64 v[140:141], v[140:141], 0, s[66:67]
	global_load_dword v112, v[140:141], off
	v_lshl_add_u64 v[140:141], v[140:141], 0, s[66:67]
	global_load_dword v113, v[140:141], off
	v_lshl_add_u64 v[140:141], v[140:141], 0, s[66:67]
	global_load_dword v114, v[140:141], off
	v_lshl_add_u64 v[140:141], v[140:141], 0, s[66:67]
	global_load_dword v115, v[140:141], off
	v_lshl_add_u64 v[140:141], v[140:141], 0, s[66:67]
	global_load_dword v116, v[140:141], off
	v_lshl_add_u64 v[140:141], v[140:141], 0, s[66:67]
	global_load_dword v117, v[140:141], off
	v_lshl_add_u64 v[140:141], v[140:141], 0, s[66:67]
	global_load_dword v118, v[140:141], off
	v_lshl_add_u64 v[140:141], v[140:141], 0, s[66:67]
	global_load_dword v119, v[140:141], off
	v_lshl_add_u64 v[140:141], v[140:141], 0, s[66:67]
	global_load_dword v120, v[140:141], off
	v_lshl_add_u64 v[140:141], v[140:141], 0, s[66:67]
	global_load_dword v121, v[140:141], off
	v_lshl_add_u64 v[140:141], v[140:141], 0, s[66:67]
	global_load_dword v122, v[140:141], off
	v_lshl_add_u64 v[140:141], v[140:141], 0, s[66:67]
	global_load_dword v123, v[140:141], off
	v_lshl_add_u64 v[140:141], v[140:141], 0, s[66:67]
	global_load_dword v124, v[140:141], off
	v_lshl_add_u64 v[140:141], v[140:141], 0, s[66:67]
	global_load_dword v125, v[140:141], off
	v_lshl_add_u64 v[140:141], v[140:141], 0, s[66:67]
	global_load_dword v126, v[140:141], off
	v_lshl_add_u64 v[140:141], v[140:141], 0, s[66:67]
	global_load_dword v127, v[140:141], off
	v_lshl_add_u64 v[140:141], v[140:141], 0, s[66:67]
	global_load_dword v128, v[140:141], off
	v_lshl_add_u64 v[140:141], v[140:141], 0, s[66:67]
	global_load_dword v129, v[140:141], off
	v_lshl_add_u64 v[140:141], v[140:141], 0, s[66:67]
	global_load_dword v130, v[140:141], off
	v_lshl_add_u64 v[140:141], v[140:141], 0, s[66:67]
	global_load_dword v131, v[140:141], off
	s_waitcnt vmcnt(28)
	ds_write_b32 v142, v100
	ds_write_b32 v142, v101 offset:264
	ds_write_b32 v142, v102 offset:528
	ds_write_b32 v142, v103 offset:792
	s_waitcnt vmcnt(24)
	ds_write_b32 v142, v104 offset:1056
	ds_write_b32 v142, v105 offset:1320
	ds_write_b32 v142, v106 offset:1584
	ds_write_b32 v142, v107 offset:1848
	s_waitcnt vmcnt(20)
	ds_write_b32 v142, v108 offset:2112
	ds_write_b32 v142, v109 offset:2376
	ds_write_b32 v142, v110 offset:2640
	ds_write_b32 v142, v111 offset:2904
	s_waitcnt vmcnt(16)
	ds_write_b32 v142, v112 offset:3168
	ds_write_b32 v142, v113 offset:3432
	ds_write_b32 v142, v114 offset:3696
	ds_write_b32 v142, v115 offset:3960
	s_waitcnt vmcnt(12)
	ds_write_b32 v142, v116 offset:4224
	ds_write_b32 v142, v117 offset:4488
	ds_write_b32 v142, v118 offset:4752
	ds_write_b32 v142, v119 offset:5016
	s_waitcnt vmcnt(8)
	ds_write_b32 v142, v120 offset:5280
	ds_write_b32 v142, v121 offset:5544
	ds_write_b32 v142, v122 offset:5808
	ds_write_b32 v142, v123 offset:6072
	s_waitcnt vmcnt(4)
	ds_write_b32 v142, v124 offset:6336
	ds_write_b32 v142, v125 offset:6600
	ds_write_b32 v142, v126 offset:6864
	ds_write_b32 v142, v127 offset:7128
	s_waitcnt vmcnt(0)
	ds_write_b32 v142, v128 offset:7392
	ds_write_b32 v142, v129 offset:7656
	ds_write_b32 v142, v130 offset:7920
	ds_write_b32 v142, v131 offset:8184
	s_waitcnt lgkmcnt(0)
	ds_read2_b32 v[6:7], v65 offset1:8
	ds_read2_b32 v[10:11], v65 offset0:33 offset1:41
	ds_read2_b32 v[12:13], v65 offset0:66 offset1:74
	ds_read2_b32 v[14:15], v65 offset0:99 offset1:107
	ds_read2_b32 v[16:17], v65 offset0:132 offset1:140
	ds_read2_b32 v[18:19], v65 offset0:165 offset1:173
	s_waitcnt lgkmcnt(5)
	v_bfe_u32 v2, v6, 16, 1
	v_add3_u32 v2, v6, v2, s41
	s_waitcnt lgkmcnt(4)
	v_bfe_u32 v3, v10, 16, 1
	v_lshrrev_b32_e32 v2, 16, v2
	v_add3_u32 v3, v10, v3, s41
	v_and_or_b32 v2, v3, s42, v2
	s_waitcnt lgkmcnt(3)
	v_bfe_u32 v3, v12, 16, 1
	v_add3_u32 v3, v12, v3, s41
	s_waitcnt lgkmcnt(2)
	v_bfe_u32 v4, v14, 16, 1
	ds_read2_b32 v[20:21], v65 offset0:198 offset1:206
	v_lshrrev_b32_e32 v3, 16, v3
	v_add3_u32 v4, v14, v4, s41
	ds_read2_b32 v[22:23], v65 offset0:231 offset1:239
	v_and_or_b32 v3, v4, s42, v3
	s_waitcnt lgkmcnt(3)
	v_bfe_u32 v4, v16, 16, 1
	v_add3_u32 v4, v16, v4, s41
	s_waitcnt lgkmcnt(2)
	v_bfe_u32 v5, v18, 16, 1
	v_lshrrev_b32_e32 v4, 16, v4
	v_add3_u32 v5, v18, v5, s41
	v_and_or_b32 v4, v5, s42, v4
	s_waitcnt lgkmcnt(1)
	v_bfe_u32 v5, v20, 16, 1
	v_or_b32_e32 v24, s6, v64
	s_ashr_i32 s9, s8, 31
	v_add3_u32 v5, v20, v5, s41
	s_waitcnt lgkmcnt(0)
	v_bfe_u32 v6, v22, 16, 1
	v_ashrrev_i32_e32 v25, 31, v24
	v_lshl_add_u64 v[8:9], s[8:9], 1, v[56:57]
	v_lshrrev_b32_e32 v5, 16, v5
	v_add3_u32 v6, v22, v6, s41
	v_lshlrev_b64 v[24:25], 13, v[24:25]
	v_and_or_b32 v5, v6, s42, v5
	v_lshl_add_u64 v[24:25], v[8:9], 0, v[24:25]
	global_store_dwordx4 v[24:25], v[2:5], off
	v_bfe_u32 v6, v23, 16, 1
	v_add3_u32 v6, v23, v6, s41
	v_bfe_u32 v2, v7, 16, 1
	v_add3_u32 v2, v7, v2, s41
	v_bfe_u32 v3, v11, 16, 1
	v_lshrrev_b32_e32 v2, 16, v2
	v_add3_u32 v3, v11, v3, s41
	v_and_or_b32 v2, v3, s42, v2
	v_bfe_u32 v3, v13, 16, 1
	v_add3_u32 v3, v13, v3, s41
	v_bfe_u32 v4, v15, 16, 1
	v_lshrrev_b32_e32 v3, 16, v3
	v_add3_u32 v4, v15, v4, s41
	v_and_or_b32 v3, v4, s42, v3
	v_bfe_u32 v4, v17, 16, 1
	v_add3_u32 v4, v17, v4, s41
	v_bfe_u32 v5, v19, 16, 1
	v_lshrrev_b32_e32 v4, 16, v4
	v_add3_u32 v5, v19, v5, s41
	v_and_or_b32 v4, v5, s42, v4
	v_bfe_u32 v5, v21, 16, 1
	v_add3_u32 v5, v21, v5, s41
	v_lshrrev_b32_e32 v5, 16, v5
	v_and_or_b32 v5, v6, s42, v5
	v_or_b32_e32 v6, s6, v66
	v_ashrrev_i32_e32 v7, 31, v6
	v_lshlrev_b64 v[6:7], 13, v[6:7]
	ds_read2_b32 v[10:11], v65 offset0:16 offset1:24
	v_lshl_add_u64 v[6:7], v[8:9], 0, v[6:7]
	global_store_dwordx4 v[6:7], v[2:5], off
	ds_read2_b32 v[6:7], v65 offset0:49 offset1:57
	ds_read2_b32 v[12:13], v65 offset0:82 offset1:90
	ds_read2_b32 v[14:15], v65 offset0:115 offset1:123
	s_waitcnt lgkmcnt(3)
	v_bfe_u32 v2, v10, 16, 1
	v_add3_u32 v2, v10, v2, s41
	s_waitcnt lgkmcnt(2)
	v_bfe_u32 v3, v6, 16, 1
	ds_read2_b32 v[16:17], v65 offset0:148 offset1:156
	v_lshrrev_b32_e32 v2, 16, v2
	v_add3_u32 v3, v6, v3, s41
	ds_read2_b32 v[18:19], v65 offset0:181 offset1:189
	v_and_or_b32 v2, v3, s42, v2
	s_waitcnt lgkmcnt(3)
	v_bfe_u32 v3, v12, 16, 1
	v_add3_u32 v3, v12, v3, s41
	s_waitcnt lgkmcnt(2)
	v_bfe_u32 v4, v14, 16, 1
	ds_read2_b32 v[20:21], v65 offset0:214 offset1:222
	v_lshrrev_b32_e32 v3, 16, v3
	v_add3_u32 v4, v14, v4, s41
	ds_read2_b32 v[22:23], v65 offset0:247 offset1:255
	v_and_or_b32 v3, v4, s42, v3
	s_waitcnt lgkmcnt(3)
	v_bfe_u32 v4, v16, 16, 1
	v_add3_u32 v4, v16, v4, s41
	s_waitcnt lgkmcnt(2)
	v_bfe_u32 v5, v18, 16, 1
	v_lshrrev_b32_e32 v4, 16, v4
	v_add3_u32 v5, v18, v5, s41
	v_and_or_b32 v4, v5, s42, v4
	s_waitcnt lgkmcnt(1)
	v_bfe_u32 v5, v20, 16, 1
	v_or_b32_e32 v24, s6, v67
	v_add3_u32 v5, v20, v5, s41
	s_waitcnt lgkmcnt(0)
	v_bfe_u32 v6, v22, 16, 1
	v_ashrrev_i32_e32 v25, 31, v24
	v_lshrrev_b32_e32 v5, 16, v5
	v_add3_u32 v6, v22, v6, s41
	v_lshlrev_b64 v[24:25], 13, v[24:25]
	v_and_or_b32 v5, v6, s42, v5
	v_lshl_add_u64 v[24:25], v[8:9], 0, v[24:25]
	global_store_dwordx4 v[24:25], v[2:5], off
	v_bfe_u32 v6, v23, 16, 1
	v_add3_u32 v6, v23, v6, s41
	v_bfe_u32 v2, v11, 16, 1
	v_add3_u32 v2, v11, v2, s41
	v_bfe_u32 v3, v7, 16, 1
	v_lshrrev_b32_e32 v2, 16, v2
	v_add3_u32 v3, v7, v3, s41
	v_and_or_b32 v2, v3, s42, v2
	v_bfe_u32 v3, v13, 16, 1
	v_add3_u32 v3, v13, v3, s41
	v_bfe_u32 v4, v15, 16, 1
	v_lshrrev_b32_e32 v3, 16, v3
	v_add3_u32 v4, v15, v4, s41
	v_and_or_b32 v3, v4, s42, v3
	v_bfe_u32 v4, v17, 16, 1
	v_add3_u32 v4, v17, v4, s41
	v_bfe_u32 v5, v19, 16, 1
	v_lshrrev_b32_e32 v4, 16, v4
	v_add3_u32 v5, v19, v5, s41
	v_and_or_b32 v4, v5, s42, v4
	v_bfe_u32 v5, v21, 16, 1
	v_add3_u32 v5, v21, v5, s41
	v_lshrrev_b32_e32 v5, 16, v5
	v_and_or_b32 v5, v6, s42, v5
	v_or_b32_e32 v6, s6, v68
	v_ashrrev_i32_e32 v7, 31, v6
	v_lshlrev_b64 v[6:7], 13, v[6:7]
	v_lshl_add_u64 v[6:7], v[8:9], 0, v[6:7]
	global_store_dwordx4 v[6:7], v[2:5], off
	s_waitcnt lgkmcnt(0)
	s_branch .LBB0_11
